# P0 bias loop: invariant bias loaded once (no per-iteration store drain); P5 router-fragment build: 48 loads in one batch instead of 4 dependent rounds
# baseline (speedup 1.0000x reference)
.LBB0_33:
	v_and_b32_e32 v0, 0x7f, v193
	v_mov_b32_e32 v3, 0
	v_mov_b32_e32 v4, s70
	v_mov_b32_e32 v5, s71
	s_add_u32 s6, s78, 0x100000
	v_or_b32_e32 v0, s0, v0
	v_mov_b32_e32 v1, v3
	s_addc_u32 s7, s79, 0
	v_lshl_add_u64 v[4:5], v[0:1], 2, v[4:5]
	v_add_u32_e32 v1, 0xfffffe00, v193
	v_add_u32_e32 v6, 0x11000, v158
	v_lshrrev_b32_e32 v7, 7, v193
	s_mov_b64 s[0:1], 0
	s_movk_i32 s8, 0x1800
	s_movk_i32 s9, 0x67f
	global_load_dword v10, v[4:5], off
	s_waitcnt vmcnt(0)
.LBB0_34:
	ds_read_b32 v11, v6
	v_add_u32_e32 v1, 0x200, v1
	v_mad_u32_u24 v2, v7, s8, v0
	v_cmp_lt_u32_e32 vcc, s9, v1
	v_add_u32_e32 v6, 0x800, v6
	v_add_u32_e32 v7, 4, v7
	v_lshl_add_u64 v[8:9], v[2:3], 2, s[6:7]
	s_or_b64 s[0:1], vcc, s[0:1]
	s_waitcnt lgkmcnt(0)
	v_add_f32_e32 v2, v11, v10
	global_store_dword v[8:9], v2, off
	s_andn2_b64 exec, exec, s[0:1]
	s_cbranch_execnz .LBB0_34
	s_or_b64 exec, exec, s[0:1]
	s_barrier

.LBB0_739:
	v_mov_b32_e32 v16, v128
	v_and_b32_e32 v0, 0x3f8, v16
	v_lshlrev_b32_e32 v4, 2, v0
	v_lshl_or_b32 v19, v0, 6, v131
	global_load_dwordx4 v[148:151], v4, s[48:49]
	global_load_dwordx4 v[152:155], v4, s[48:49] offset:16
	global_load_dwordx4 v[156:159], v4, s[74:75] offset:16
	global_load_dwordx4 v[160:163], v4, s[74:75]
	v_or_b32_e32 v20, 0x40, v19
	v_or_b32_e32 v21, 0x80, v19
	v_or_b32_e32 v22, 0xc0, v19
	v_or_b32_e32 v23, 0x100, v19
	v_or_b32_e32 v24, 0x140, v19
	v_or_b32_e32 v25, 0x180, v19
	v_or_b32_e32 v26, 0x1c0, v19
	global_load_dword v164, v19, s[44:45]
	global_load_dword v165, v20, s[44:45]
	global_load_dword v166, v21, s[44:45]
	global_load_dword v167, v22, s[44:45]
	global_load_dword v168, v23, s[44:45]
	global_load_dword v169, v24, s[44:45]
	global_load_dword v170, v25, s[44:45]
	global_load_dword v171, v26, s[44:45]
	v_add_u32_e32 v16, 0x100, v128
	v_and_b32_e32 v0, 0x3f8, v16
	v_lshlrev_b32_e32 v4, 2, v0
	v_lshl_or_b32 v19, v0, 6, v131
	global_load_dwordx4 v[196:199], v4, s[48:49]
	global_load_dwordx4 v[200:203], v4, s[48:49] offset:16
	global_load_dwordx4 v[204:207], v4, s[74:75] offset:16
	global_load_dwordx4 v[208:211], v4, s[74:75]
	v_or_b32_e32 v20, 0x40, v19
	v_or_b32_e32 v21, 0x80, v19
	v_or_b32_e32 v22, 0xc0, v19
	v_or_b32_e32 v23, 0x100, v19
	v_or_b32_e32 v24, 0x140, v19
	v_or_b32_e32 v25, 0x180, v19
	v_or_b32_e32 v26, 0x1c0, v19
	global_load_dword v212, v19, s[44:45]
	global_load_dword v213, v20, s[44:45]
	global_load_dword v214, v21, s[44:45]
	global_load_dword v215, v22, s[44:45]
	global_load_dword v216, v23, s[44:45]
	global_load_dword v217, v24, s[44:45]
	global_load_dword v218, v25, s[44:45]
	global_load_dword v219, v26, s[44:45]
	v_add_u32_e32 v16, 0x200, v128
	v_and_b32_e32 v0, 0x3f8, v16
	v_lshlrev_b32_e32 v4, 2, v0
	v_lshl_or_b32 v19, v0, 6, v131
	global_load_dwordx4 v[220:223], v4, s[48:49]
	global_load_dwordx4 v[224:227], v4, s[48:49] offset:16
	global_load_dwordx4 v[228:231], v4, s[74:75] offset:16
	global_load_dwordx4 v[232:235], v4, s[74:75]
	v_or_b32_e32 v20, 0x40, v19
	v_or_b32_e32 v21, 0x80, v19
	v_or_b32_e32 v22, 0xc0, v19
	v_or_b32_e32 v23, 0x100, v19
	v_or_b32_e32 v24, 0x140, v19
	v_or_b32_e32 v25, 0x180, v19
	v_or_b32_e32 v26, 0x1c0, v19
	global_load_dword v236, v19, s[44:45]
	global_load_dword v237, v20, s[44:45]
	global_load_dword v238, v21, s[44:45]
	global_load_dword v239, v22, s[44:45]
	global_load_dword v240, v23, s[44:45]
	global_load_dword v241, v24, s[44:45]
	global_load_dword v242, v25, s[44:45]
	global_load_dword v243, v26, s[44:45]
	v_add_u32_e32 v16, 0x300, v128
	v_and_b32_e32 v0, 0x3f8, v16
	v_lshlrev_b32_e32 v4, 2, v0
	v_lshl_or_b32 v19, v0, 6, v131
	global_load_dwordx4 v[172:175], v4, s[48:49]
	global_load_dwordx4 v[176:179], v4, s[48:49] offset:16
	global_load_dwordx4 v[180:183], v4, s[74:75] offset:16
	global_load_dwordx4 v[184:187], v4, s[74:75]
	v_or_b32_e32 v20, 0x40, v19
	v_or_b32_e32 v21, 0x80, v19
	v_or_b32_e32 v22, 0xc0, v19
	v_or_b32_e32 v23, 0x100, v19
	v_or_b32_e32 v24, 0x140, v19
	v_or_b32_e32 v25, 0x180, v19
	v_or_b32_e32 v26, 0x1c0, v19
	global_load_dword v188, v19, s[44:45]
	global_load_dword v189, v20, s[44:45]
	global_load_dword v190, v21, s[44:45]
	global_load_dword v191, v22, s[44:45]
	global_load_dword v246, v23, s[44:45]
	global_load_dword v247, v24, s[44:45]
	global_load_dword v248, v25, s[44:45]
	global_load_dword v249, v26, s[44:45]
	s_waitcnt vmcnt(0)
	v_add_f32_e32 v12, 1.0, v148
	v_add_f32_e32 v13, 1.0, v149
	v_add_f32_e32 v14, 1.0, v150
	v_add_f32_e32 v15, 1.0, v151
	v_add_f32_e32 v8, 1.0, v152
	v_add_f32_e32 v9, 1.0, v153
	v_add_f32_e32 v10, 1.0, v154
	v_add_f32_e32 v11, 1.0, v155
	v_mul_f32_e32 v4, v160, v12
	v_mul_f32_e32 v5, v161, v13
	v_mul_f32_e32 v6, v162, v14
	v_mul_f32_e32 v7, v163, v15
	v_mul_f32_e32 v8, v156, v8
	v_mul_f32_e32 v9, v157, v9
	v_mul_f32_e32 v10, v158, v10
	v_mul_f32_e32 v11, v159, v11
	v_mul_f32_e32 v0, v164, v4
	v_mul_f32_e32 v1, v165, v5
	v_mul_f32_e32 v2, v166, v6
	v_mul_f32_e32 v3, v167, v7
	v_mul_f32_e32 v12, v168, v8
	v_mul_f32_e32 v13, v169, v9
	v_mul_f32_e32 v14, v170, v10
	v_mul_f32_e32 v15, v171, v11
	v_cvt_pk_bf16_f32 v0, v0, v1
	v_cvt_pk_bf16_f32 v1, v2, v3
	v_cvt_pk_bf16_f32 v2, v12, v13
	v_cvt_pk_bf16_f32 v3, v14, v15
	ds_write_b128 v127, v[0:3] offset:0
	v_lshlrev_b32_e32 v12, 16, v0
	v_and_b32_e32 v13, 0xffff0000, v0
	v_lshlrev_b32_e32 v14, 16, v1
	v_and_b32_e32 v15, 0xffff0000, v1
	v_lshlrev_b32_e32 v27, 16, v2
	v_and_b32_e32 v28, 0xffff0000, v2
	v_lshlrev_b32_e32 v29, 16, v3
	v_and_b32_e32 v30, 0xffff0000, v3
	s_nop 1
	v_fma_f32 v0, v164, v4, -v12
	v_fma_f32 v1, v165, v5, -v13
	v_fma_f32 v2, v166, v6, -v14
	v_fma_f32 v3, v167, v7, -v15
	v_fma_f32 v4, v168, v8, -v27
	v_fma_f32 v5, v169, v9, -v28
	v_fma_f32 v6, v170, v10, -v29
	v_fma_f32 v7, v171, v11, -v30
	v_cvt_pk_bf16_f32 v0, v0, v1
	v_cvt_pk_bf16_f32 v1, v2, v3
	v_cvt_pk_bf16_f32 v2, v4, v5
	v_cvt_pk_bf16_f32 v3, v6, v7
	ds_write_b128 v127, v[0:3] offset:32768
	s_nop 1
	v_add_f32_e32 v12, 1.0, v196
	v_add_f32_e32 v13, 1.0, v197
	v_add_f32_e32 v14, 1.0, v198
	v_add_f32_e32 v15, 1.0, v199
	v_add_f32_e32 v8, 1.0, v200
	v_add_f32_e32 v9, 1.0, v201
	v_add_f32_e32 v10, 1.0, v202
	v_add_f32_e32 v11, 1.0, v203
	v_mul_f32_e32 v4, v208, v12
	v_mul_f32_e32 v5, v209, v13
	v_mul_f32_e32 v6, v210, v14
	v_mul_f32_e32 v7, v211, v15
	v_mul_f32_e32 v8, v204, v8
	v_mul_f32_e32 v9, v205, v9
	v_mul_f32_e32 v10, v206, v10
	v_mul_f32_e32 v11, v207, v11
	v_mul_f32_e32 v0, v212, v4
	v_mul_f32_e32 v1, v213, v5
	v_mul_f32_e32 v2, v214, v6
	v_mul_f32_e32 v3, v215, v7
	v_mul_f32_e32 v12, v216, v8
	v_mul_f32_e32 v13, v217, v9
	v_mul_f32_e32 v14, v218, v10
	v_mul_f32_e32 v15, v219, v11
	v_cvt_pk_bf16_f32 v0, v0, v1
	v_cvt_pk_bf16_f32 v1, v2, v3
	v_cvt_pk_bf16_f32 v2, v12, v13
	v_cvt_pk_bf16_f32 v3, v14, v15
	ds_write_b128 v127, v[0:3] offset:8192
	v_lshlrev_b32_e32 v12, 16, v0
	v_and_b32_e32 v13, 0xffff0000, v0
	v_lshlrev_b32_e32 v14, 16, v1
	v_and_b32_e32 v15, 0xffff0000, v1
	v_lshlrev_b32_e32 v27, 16, v2
	v_and_b32_e32 v28, 0xffff0000, v2
	v_lshlrev_b32_e32 v29, 16, v3
	v_and_b32_e32 v30, 0xffff0000, v3
	s_nop 1
	v_fma_f32 v0, v212, v4, -v12
	v_fma_f32 v1, v213, v5, -v13
	v_fma_f32 v2, v214, v6, -v14
	v_fma_f32 v3, v215, v7, -v15
	v_fma_f32 v4, v216, v8, -v27
	v_fma_f32 v5, v217, v9, -v28
	v_fma_f32 v6, v218, v10, -v29
	v_fma_f32 v7, v219, v11, -v30
	v_cvt_pk_bf16_f32 v0, v0, v1
	v_cvt_pk_bf16_f32 v1, v2, v3
	v_cvt_pk_bf16_f32 v2, v4, v5
	v_cvt_pk_bf16_f32 v3, v6, v7
	ds_write_b128 v127, v[0:3] offset:40960
	s_nop 1
	v_add_f32_e32 v12, 1.0, v220
	v_add_f32_e32 v13, 1.0, v221
	v_add_f32_e32 v14, 1.0, v222
	v_add_f32_e32 v15, 1.0, v223
	v_add_f32_e32 v8, 1.0, v224
	v_add_f32_e32 v9, 1.0, v225
	v_add_f32_e32 v10, 1.0, v226
	v_add_f32_e32 v11, 1.0, v227
	v_mul_f32_e32 v4, v232, v12
	v_mul_f32_e32 v5, v233, v13
	v_mul_f32_e32 v6, v234, v14
	v_mul_f32_e32 v7, v235, v15
	v_mul_f32_e32 v8, v228, v8
	v_mul_f32_e32 v9, v229, v9
	v_mul_f32_e32 v10, v230, v10
	v_mul_f32_e32 v11, v231, v11
	v_mul_f32_e32 v0, v236, v4
	v_mul_f32_e32 v1, v237, v5
	v_mul_f32_e32 v2, v238, v6
	v_mul_f32_e32 v3, v239, v7
	v_mul_f32_e32 v12, v240, v8
	v_mul_f32_e32 v13, v241, v9
	v_mul_f32_e32 v14, v242, v10
	v_mul_f32_e32 v15, v243, v11
	v_cvt_pk_bf16_f32 v0, v0, v1
	v_cvt_pk_bf16_f32 v1, v2, v3
	v_cvt_pk_bf16_f32 v2, v12, v13
	v_cvt_pk_bf16_f32 v3, v14, v15
	ds_write_b128 v127, v[0:3] offset:16384
	v_lshlrev_b32_e32 v12, 16, v0
	v_and_b32_e32 v13, 0xffff0000, v0
	v_lshlrev_b32_e32 v14, 16, v1
	v_and_b32_e32 v15, 0xffff0000, v1
	v_lshlrev_b32_e32 v27, 16, v2
	v_and_b32_e32 v28, 0xffff0000, v2
	v_lshlrev_b32_e32 v29, 16, v3
	v_and_b32_e32 v30, 0xffff0000, v3
	s_nop 1
	v_fma_f32 v0, v236, v4, -v12
	v_fma_f32 v1, v237, v5, -v13
	v_fma_f32 v2, v238, v6, -v14
	v_fma_f32 v3, v239, v7, -v15
	v_fma_f32 v4, v240, v8, -v27
	v_fma_f32 v5, v241, v9, -v28
	v_fma_f32 v6, v242, v10, -v29
	v_fma_f32 v7, v243, v11, -v30
	v_cvt_pk_bf16_f32 v0, v0, v1
	v_cvt_pk_bf16_f32 v1, v2, v3
	v_cvt_pk_bf16_f32 v2, v4, v5
	v_cvt_pk_bf16_f32 v3, v6, v7
	ds_write_b128 v127, v[0:3] offset:49152
	s_nop 1
	v_add_f32_e32 v12, 1.0, v172
	v_add_f32_e32 v13, 1.0, v173
	v_add_f32_e32 v14, 1.0, v174
	v_add_f32_e32 v15, 1.0, v175
	v_add_f32_e32 v8, 1.0, v176
	v_add_f32_e32 v9, 1.0, v177
	v_add_f32_e32 v10, 1.0, v178
	v_add_f32_e32 v11, 1.0, v179
	v_mul_f32_e32 v4, v184, v12
	v_mul_f32_e32 v5, v185, v13
	v_mul_f32_e32 v6, v186, v14
	v_mul_f32_e32 v7, v187, v15
	v_mul_f32_e32 v8, v180, v8
	v_mul_f32_e32 v9, v181, v9
	v_mul_f32_e32 v10, v182, v10
	v_mul_f32_e32 v11, v183, v11
	v_mul_f32_e32 v0, v188, v4
	v_mul_f32_e32 v1, v189, v5
	v_mul_f32_e32 v2, v190, v6
	v_mul_f32_e32 v3, v191, v7
	v_mul_f32_e32 v12, v246, v8
	v_mul_f32_e32 v13, v247, v9
	v_mul_f32_e32 v14, v248, v10
	v_mul_f32_e32 v15, v249, v11
	v_cvt_pk_bf16_f32 v0, v0, v1
	v_cvt_pk_bf16_f32 v1, v2, v3
	v_cvt_pk_bf16_f32 v2, v12, v13
	v_cvt_pk_bf16_f32 v3, v14, v15
	ds_write_b128 v127, v[0:3] offset:24576
	v_lshlrev_b32_e32 v12, 16, v0
	v_and_b32_e32 v13, 0xffff0000, v0
	v_lshlrev_b32_e32 v14, 16, v1
	v_and_b32_e32 v15, 0xffff0000, v1
	v_lshlrev_b32_e32 v27, 16, v2
	v_and_b32_e32 v28, 0xffff0000, v2
	v_lshlrev_b32_e32 v29, 16, v3
	v_and_b32_e32 v30, 0xffff0000, v3
	s_nop 1
	v_fma_f32 v0, v188, v4, -v12
	v_fma_f32 v1, v189, v5, -v13
	v_fma_f32 v2, v190, v6, -v14
	v_fma_f32 v3, v191, v7, -v15
	v_fma_f32 v4, v246, v8, -v27
	v_fma_f32 v5, v247, v9, -v28
	v_fma_f32 v6, v248, v10, -v29
	v_fma_f32 v7, v249, v11, -v30
	v_cvt_pk_bf16_f32 v0, v0, v1
	v_cvt_pk_bf16_f32 v1, v2, v3
	v_cvt_pk_bf16_f32 v2, v4, v5
	v_cvt_pk_bf16_f32 v3, v6, v7
	ds_write_b128 v127, v[0:3] offset:57344
	s_nop 1
	s_or_b64 exec, exec, s[52:53]
	s_andn2_b64 vcc, exec, s[40:41]
	s_cbranch_vccnz .LBB0_776
	v_mov_b32_e32 v16, 0
	v_lshl_add_u64 v[2:3], s[50:51], 2, v[94:95]
	s_mov_b64 s[50:51], 0
	v_mov_b32_e32 v17, v16
	v_mov_b32_e32 v14, v16
	v_mov_b32_e32 v15, v16
	v_mov_b32_e32 v12, v16
	v_mov_b32_e32 v13, v16
	v_mov_b32_e32 v10, v16
	v_mov_b32_e32 v11, v16
	v_mov_b32_e32 v8, v16
	v_mov_b32_e32 v9, v16
	v_mov_b32_e32 v6, v16
	v_mov_b32_e32 v7, v16
	v_mov_b32_e32 v4, v16
	v_mov_b32_e32 v5, v16
	v_mov_b32_e32 v0, v16
	v_mov_b32_e32 v1, v16
